# P3 MoBA gating: the guarded key-mean loads of an item issued together under nested lane masks, one wait
# speedup vs baseline: 1.0236x; 1.0014x over previous
; DI void phase3(const Params& P, char* smem) {
;     ...
;     for (int item0 = RBLK * 2; item0 < 1024; item0 += RGRID * 2) {
;       const int item = item0 + VHALF;
;       const int bh = item >> 5, own = (item & 512) ? 31 - (item & 31) : (item & 31), b = bh >> 3, h = bh & 7, tid = VT;
;       const bool act = own > 0;
;       if (act) for (int i = tid; i < own * 64; i += 256) km[i] = kmean[bh * 32 * 64 + i];
;       if (tid < 32) cnt[tid] = 0;
;       __syncthreads();
.LBB0_651:
	v_add_u32_e32 v25, s22, v190
	v_and_b32_e32 v0, 0x200, v25
	v_and_b32_e32 v2, 31, v25
	v_bitop3_b32 v3, v25, 31, v25 bitop3:0xc
	v_cmp_eq_u32_e64 s[0:1], 0, v0
	s_nop 1
	v_cndmask_b32_e64 v26, v3, v2, s[0:1]
	v_cmp_ne_u32_e64 s[4:5], 0, v26
	s_and_saveexec_b64 s[6:7], s[4:5]
	s_cbranch_execz .LBB0_661
	v_lshlrev_b32_e32 v0, 6, v26
	v_cmp_lt_u32_e64 s[0:1], v191, v0
	s_and_b64 exec, exec, s[0:1]
	s_cbranch_execz .LBB0_661
	v_lshlrev_b32_e32 v2, 6, v25
	v_and_b32_e32 v2, 0xfffff800, v2
	s_mov_b64 s[32:33], exec
	v_or_b32_e32 v4, v191, v2
	v_ashrrev_i32_e32 v5, 31, v4
	v_lshl_add_u64 v[4:5], v[4:5], 2, s[20:21]
	global_load_dword v210, v[4:5], off
	v_cmp_lt_u32_e64 s[0:1], v15, v0
	s_and_b64 exec, exec, s[0:1]
	s_mov_b64 s[34:35], exec
	v_or_b32_e32 v4, v15, v2
	v_ashrrev_i32_e32 v5, 31, v4
	v_lshl_add_u64 v[4:5], v[4:5], 2, s[20:21]
	global_load_dword v211, v[4:5], off
	v_cmp_lt_u32_e64 s[0:1], v16, v0
	s_and_b64 exec, exec, s[0:1]
	s_mov_b64 s[36:37], exec
	v_or_b32_e32 v4, v16, v2
	v_ashrrev_i32_e32 v5, 31, v4
	v_lshl_add_u64 v[4:5], v[4:5], 2, s[20:21]
	global_load_dword v212, v[4:5], off
	v_cmp_lt_u32_e64 s[0:1], v17, v0
	s_and_b64 exec, exec, s[0:1]
	s_mov_b64 s[38:39], exec
	v_or_b32_e32 v4, v17, v2
	v_ashrrev_i32_e32 v5, 31, v4
	v_lshl_add_u64 v[4:5], v[4:5], 2, s[20:21]
	global_load_dword v213, v[4:5], off
	v_cmp_lt_u32_e64 s[0:1], v19, v0
	s_and_b64 exec, exec, s[0:1]
	s_mov_b64 s[40:41], exec
	v_or_b32_e32 v4, v19, v2
	v_ashrrev_i32_e32 v5, 31, v4
	v_lshl_add_u64 v[4:5], v[4:5], 2, s[20:21]
	global_load_dword v214, v[4:5], off
	v_cmp_lt_u32_e64 s[0:1], v20, v0
	s_and_b64 exec, exec, s[0:1]
	s_mov_b64 s[42:43], exec
	v_or_b32_e32 v4, v20, v2
	v_ashrrev_i32_e32 v5, 31, v4
	v_lshl_add_u64 v[4:5], v[4:5], 2, s[20:21]
	global_load_dword v215, v[4:5], off
	v_cmp_lt_u32_e64 s[0:1], v21, v0
	s_and_b64 exec, exec, s[0:1]
	s_mov_b64 s[44:45], exec
	v_or_b32_e32 v4, v21, v2
	v_ashrrev_i32_e32 v5, 31, v4
	v_lshl_add_u64 v[4:5], v[4:5], 2, s[20:21]
	global_load_dword v216, v[4:5], off
	v_cmp_lt_u32_e64 s[0:1], v22, v0
	s_and_b64 exec, exec, s[0:1]
	s_mov_b64 s[46:47], exec
	v_or_b32_e32 v4, v22, v2
	v_ashrrev_i32_e32 v5, 31, v4
	v_lshl_add_u64 v[4:5], v[4:5], 2, s[20:21]
	global_load_dword v217, v[4:5], off
	s_waitcnt vmcnt(0)
	s_mov_b64 exec, s[32:33]
	ds_write_b32 v14, v210
	s_mov_b64 exec, s[34:35]
	ds_write_b32 v14, v211 offset:1024
	s_mov_b64 exec, s[36:37]
	ds_write_b32 v14, v212 offset:2048
	s_mov_b64 exec, s[38:39]
	ds_write_b32 v18, v213
	s_mov_b64 exec, s[40:41]
	ds_write_b32 v14, v214 offset:4096
	s_mov_b64 exec, s[42:43]
	ds_write_b32 v14, v215 offset:5120
	s_mov_b64 exec, s[44:45]
	ds_write_b32 v14, v216 offset:6144
	s_mov_b64 exec, s[46:47]
	ds_write_b32 v23, v217
